# SwiGLU epilogue of the up GEMMs rewritten with packed f32 math (v_pk_mul/v_pk_add), 4 pairs staged to hide trans latency, same op order per element
# speedup vs baseline: 1.0029x; 1.0022x over previous
; __device__ __forceinline__ unsigned pk2(float lo, float hi) { return pg8::cvt_pk_bf16(lo, hi); }
; __device__ __forceinline__ float sigm(float x) { return __builtin_amdgcn_rcpf(1.f + __expf(-x)); }
;     __device__ __forceinline__ void operator()(const f32x4 (&acc)[2][2][4][2], const pg8::Unit& u, int wr, int wc, int fr, int fq) const {
;     ...
;         const int row0 = u.pm * 256 + wr * 64 + fr, col0 = u.pn * 128 + wc * 32 + 8 * fq;
; #pragma unroll
;         for (int ai = 0; ai < 2; ++ai)
; #pragma unroll
;             for (int m = 0; m < 4; ++m) {
;                 bf16_t* rowp = O + (size_t)(row0 + ai * 128 + m * 16) * DFF + col0;
;                 float v[8];
; #pragma unroll
;                 for (int n = 0; n < 2; ++n)
; #pragma unroll
;                     for (int j = 0; j < 4; ++j) { const float g = acc[ai][0][m][n][j], up = acc[ai][1][m][n][j]; v[n * 4 + j] = g * sigm(g) * up; }
;                 u32x4 w; w.x = pk2(v[0], v[1]); w.y = pk2(v[2], v[3]); w.z = pk2(v[4], v[5]); w.w = pk2(v[6], v[7]);
;                 *(u32x4*)rowp = w;
;             }
.LBB0_472:
	v_mov_b32_e32 v228, 0xbfb8aa3b
	v_pk_mul_f32 v[210:211], v[124:125], v[228:229] op_sel_hi:[1,0]
	v_pk_mul_f32 v[212:213], v[126:127], v[228:229] op_sel_hi:[1,0]
	v_pk_mul_f32 v[214:215], v[116:117], v[228:229] op_sel_hi:[1,0]
	v_pk_mul_f32 v[216:217], v[118:119], v[228:229] op_sel_hi:[1,0]
	v_exp_f32_e32 v210, v210
	v_exp_f32_e32 v211, v211
	v_exp_f32_e32 v212, v212
	v_exp_f32_e32 v213, v213
	v_exp_f32_e32 v214, v214
	v_exp_f32_e32 v215, v215
	v_exp_f32_e32 v216, v216
	v_exp_f32_e32 v217, v217
	v_pk_add_f32 v[210:211], v[210:211], 1.0 op_sel_hi:[1,0]
	v_pk_add_f32 v[212:213], v[212:213], 1.0 op_sel_hi:[1,0]
	v_pk_add_f32 v[214:215], v[214:215], 1.0 op_sel_hi:[1,0]
	v_pk_add_f32 v[216:217], v[216:217], 1.0 op_sel_hi:[1,0]
	v_rcp_f32_e32 v210, v210
	v_rcp_f32_e32 v211, v211
	v_rcp_f32_e32 v212, v212
	v_rcp_f32_e32 v213, v213
	v_rcp_f32_e32 v214, v214
	v_rcp_f32_e32 v215, v215
	v_rcp_f32_e32 v216, v216
	v_rcp_f32_e32 v217, v217
	v_pk_mul_f32 v[210:211], v[124:125], v[210:211]
	v_pk_mul_f32 v[212:213], v[126:127], v[212:213]
	v_pk_mul_f32 v[214:215], v[116:117], v[214:215]
	v_pk_mul_f32 v[216:217], v[118:119], v[216:217]
	v_pk_mul_f32 v[218:219], v[210:211], v[120:121]
	v_pk_mul_f32 v[220:221], v[212:213], v[122:123]
	v_pk_mul_f32 v[222:223], v[214:215], v[112:113]
	v_pk_mul_f32 v[224:225], v[216:217], v[114:115]
	v_lshl_or_b32 v128, s62, 7, v135
	v_readlane_b32 s42, v255, 21
	v_ashrrev_i32_e32 v129, 31, v128
	v_readlane_b32 s43, v255, 22
	v_lshl_add_u32 v138, s63, 8, v134
	s_movk_i32 s19, 0x1600
	s_nop 1
	v_lshl_add_u64 v[128:129], v[128:129], 1, s[42:43]
	s_andn2_b64 vcc, exec, s[52:53]
	v_mad_i64_i32 v[116:117], s[42:43], v138, s19, v[128:129]
	v_cvt_pk_bf16_f32 v112, v218, v219
	v_cvt_pk_bf16_f32 v113, v220, v221
	v_cvt_pk_bf16_f32 v114, v222, v223
	v_cvt_pk_bf16_f32 v115, v224, v225
	global_store_dwordx4 v[116:117], v[112:115], off
	s_nop 1
	v_pk_mul_f32 v[210:211], v[108:109], v[228:229] op_sel_hi:[1,0]
	v_pk_mul_f32 v[212:213], v[110:111], v[228:229] op_sel_hi:[1,0]
	v_pk_mul_f32 v[214:215], v[100:101], v[228:229] op_sel_hi:[1,0]
	v_pk_mul_f32 v[216:217], v[102:103], v[228:229] op_sel_hi:[1,0]
	v_exp_f32_e32 v210, v210
	v_exp_f32_e32 v211, v211
	v_exp_f32_e32 v212, v212
	v_exp_f32_e32 v213, v213
	v_exp_f32_e32 v214, v214
	v_exp_f32_e32 v215, v215
	v_exp_f32_e32 v216, v216
	v_exp_f32_e32 v217, v217
	v_pk_add_f32 v[210:211], v[210:211], 1.0 op_sel_hi:[1,0]
	v_pk_add_f32 v[212:213], v[212:213], 1.0 op_sel_hi:[1,0]
	v_pk_add_f32 v[214:215], v[214:215], 1.0 op_sel_hi:[1,0]
	v_pk_add_f32 v[216:217], v[216:217], 1.0 op_sel_hi:[1,0]
	v_rcp_f32_e32 v210, v210
	v_rcp_f32_e32 v211, v211
	v_rcp_f32_e32 v212, v212
	v_rcp_f32_e32 v213, v213
	v_rcp_f32_e32 v214, v214
	v_rcp_f32_e32 v215, v215
	v_rcp_f32_e32 v216, v216
	v_rcp_f32_e32 v217, v217
	v_pk_mul_f32 v[210:211], v[108:109], v[210:211]
	v_pk_mul_f32 v[212:213], v[110:111], v[212:213]
	v_pk_mul_f32 v[214:215], v[100:101], v[214:215]
	v_pk_mul_f32 v[216:217], v[102:103], v[216:217]
	v_pk_mul_f32 v[218:219], v[210:211], v[104:105]
	v_pk_mul_f32 v[220:221], v[212:213], v[106:107]
	v_pk_mul_f32 v[222:223], v[214:215], v[96:97]
	v_pk_mul_f32 v[224:225], v[216:217], v[98:99]
	v_or_b32_e32 v112, 16, v138
	v_mad_i64_i32 v[100:101], s[42:43], v112, s19, v[128:129]
	v_cvt_pk_bf16_f32 v96, v218, v219
	v_cvt_pk_bf16_f32 v97, v220, v221
	v_cvt_pk_bf16_f32 v98, v222, v223
	v_cvt_pk_bf16_f32 v99, v224, v225
	global_store_dwordx4 v[100:101], v[96:99], off
	s_nop 1
	v_pk_mul_f32 v[210:211], v[92:93], v[228:229] op_sel_hi:[1,0]
	v_pk_mul_f32 v[212:213], v[94:95], v[228:229] op_sel_hi:[1,0]
	v_pk_mul_f32 v[214:215], v[84:85], v[228:229] op_sel_hi:[1,0]
	v_pk_mul_f32 v[216:217], v[86:87], v[228:229] op_sel_hi:[1,0]
	v_exp_f32_e32 v210, v210
	v_exp_f32_e32 v211, v211
	v_exp_f32_e32 v212, v212
	v_exp_f32_e32 v213, v213
	v_exp_f32_e32 v214, v214
	v_exp_f32_e32 v215, v215
	v_exp_f32_e32 v216, v216
	v_exp_f32_e32 v217, v217
	v_pk_add_f32 v[210:211], v[210:211], 1.0 op_sel_hi:[1,0]
	v_pk_add_f32 v[212:213], v[212:213], 1.0 op_sel_hi:[1,0]
	v_pk_add_f32 v[214:215], v[214:215], 1.0 op_sel_hi:[1,0]
	v_pk_add_f32 v[216:217], v[216:217], 1.0 op_sel_hi:[1,0]
	v_rcp_f32_e32 v210, v210
	v_rcp_f32_e32 v211, v211
	v_rcp_f32_e32 v212, v212
	v_rcp_f32_e32 v213, v213
	v_rcp_f32_e32 v214, v214
	v_rcp_f32_e32 v215, v215
	v_rcp_f32_e32 v216, v216
	v_rcp_f32_e32 v217, v217
	v_pk_mul_f32 v[210:211], v[92:93], v[210:211]
	v_pk_mul_f32 v[212:213], v[94:95], v[212:213]
	v_pk_mul_f32 v[214:215], v[84:85], v[214:215]
	v_pk_mul_f32 v[216:217], v[86:87], v[216:217]
	v_pk_mul_f32 v[218:219], v[210:211], v[88:89]
	v_pk_mul_f32 v[220:221], v[212:213], v[90:91]
	v_pk_mul_f32 v[222:223], v[214:215], v[80:81]
	v_pk_mul_f32 v[224:225], v[216:217], v[82:83]
	v_or_b32_e32 v96, 32, v138
	v_mad_i64_i32 v[84:85], s[42:43], v96, s19, v[128:129]
	v_cvt_pk_bf16_f32 v80, v218, v219
	v_cvt_pk_bf16_f32 v81, v220, v221
	v_cvt_pk_bf16_f32 v82, v222, v223
	v_cvt_pk_bf16_f32 v83, v224, v225
	global_store_dwordx4 v[84:85], v[80:83], off
	s_nop 1
	v_pk_mul_f32 v[210:211], v[76:77], v[228:229] op_sel_hi:[1,0]
	v_pk_mul_f32 v[212:213], v[78:79], v[228:229] op_sel_hi:[1,0]
	v_pk_mul_f32 v[214:215], v[68:69], v[228:229] op_sel_hi:[1,0]
	v_pk_mul_f32 v[216:217], v[70:71], v[228:229] op_sel_hi:[1,0]
	v_exp_f32_e32 v210, v210
	v_exp_f32_e32 v211, v211
	v_exp_f32_e32 v212, v212
	v_exp_f32_e32 v213, v213
	v_exp_f32_e32 v214, v214
	v_exp_f32_e32 v215, v215
	v_exp_f32_e32 v216, v216
	v_exp_f32_e32 v217, v217
	v_pk_add_f32 v[210:211], v[210:211], 1.0 op_sel_hi:[1,0]
	v_pk_add_f32 v[212:213], v[212:213], 1.0 op_sel_hi:[1,0]
	v_pk_add_f32 v[214:215], v[214:215], 1.0 op_sel_hi:[1,0]
; __device__ __forceinline__ unsigned pk2(float lo, float hi) { return pg8::cvt_pk_bf16(lo, hi); }
; __device__ __forceinline__ float sigm(float x) { return __builtin_amdgcn_rcpf(1.f + __expf(-x)); }
;     __device__ __forceinline__ void operator()(const f32x4 (&acc)[2][2][4][2], const pg8::Unit& u, int wr, int wc, int fr, int fq) const {
;     ...
;         const int row0 = u.pm * 256 + wr * 64 + fr, col0 = u.pn * 128 + wc * 32 + 8 * fq;
; #pragma unroll
;         for (int ai = 0; ai < 2; ++ai)
; #pragma unroll
;             for (int m = 0; m < 4; ++m) {
;                 bf16_t* rowp = O + (size_t)(row0 + ai * 128 + m * 16) * DFF + col0;
;                 float v[8];
; #pragma unroll
;                 for (int n = 0; n < 2; ++n)
; #pragma unroll
;                     for (int j = 0; j < 4; ++j) { const float g = acc[ai][0][m][n][j], up = acc[ai][1][m][n][j]; v[n * 4 + j] = g * sigm(g) * up; }
;                 u32x4 w; w.x = pk2(v[0], v[1]); w.y = pk2(v[2], v[3]); w.z = pk2(v[4], v[5]); w.w = pk2(v[6], v[7]);
;                 *(u32x4*)rowp = w;
;             }
	v_pk_add_f32 v[216:217], v[216:217], 1.0 op_sel_hi:[1,0]
	v_rcp_f32_e32 v210, v210
	v_rcp_f32_e32 v211, v211
	v_rcp_f32_e32 v212, v212
	v_rcp_f32_e32 v213, v213
	v_rcp_f32_e32 v214, v214
	v_rcp_f32_e32 v215, v215
	v_rcp_f32_e32 v216, v216
	v_rcp_f32_e32 v217, v217
	v_pk_mul_f32 v[210:211], v[76:77], v[210:211]
	v_pk_mul_f32 v[212:213], v[78:79], v[212:213]
	v_pk_mul_f32 v[214:215], v[68:69], v[214:215]
	v_pk_mul_f32 v[216:217], v[70:71], v[216:217]
	v_pk_mul_f32 v[218:219], v[210:211], v[72:73]
	v_pk_mul_f32 v[220:221], v[212:213], v[74:75]
	v_pk_mul_f32 v[222:223], v[214:215], v[64:65]
	v_pk_mul_f32 v[224:225], v[216:217], v[66:67]
	v_or_b32_e32 v80, 48, v138
	v_mad_i64_i32 v[68:69], s[42:43], v80, s19, v[128:129]
	v_cvt_pk_bf16_f32 v64, v218, v219
	v_cvt_pk_bf16_f32 v65, v220, v221
	v_cvt_pk_bf16_f32 v66, v222, v223
	v_cvt_pk_bf16_f32 v67, v224, v225
	global_store_dwordx4 v[68:69], v[64:67], off
	s_nop 1
	v_pk_mul_f32 v[210:211], v[60:61], v[228:229] op_sel_hi:[1,0]
	v_pk_mul_f32 v[212:213], v[62:63], v[228:229] op_sel_hi:[1,0]
	v_pk_mul_f32 v[214:215], v[52:53], v[228:229] op_sel_hi:[1,0]
	v_pk_mul_f32 v[216:217], v[54:55], v[228:229] op_sel_hi:[1,0]
	v_exp_f32_e32 v210, v210
	v_exp_f32_e32 v211, v211
	v_exp_f32_e32 v212, v212
	v_exp_f32_e32 v213, v213
	v_exp_f32_e32 v214, v214
	v_exp_f32_e32 v215, v215
	v_exp_f32_e32 v216, v216
	v_exp_f32_e32 v217, v217
	v_pk_add_f32 v[210:211], v[210:211], 1.0 op_sel_hi:[1,0]
	v_pk_add_f32 v[212:213], v[212:213], 1.0 op_sel_hi:[1,0]
	v_pk_add_f32 v[214:215], v[214:215], 1.0 op_sel_hi:[1,0]
	v_pk_add_f32 v[216:217], v[216:217], 1.0 op_sel_hi:[1,0]
	v_rcp_f32_e32 v210, v210
	v_rcp_f32_e32 v211, v211
	v_rcp_f32_e32 v212, v212
	v_rcp_f32_e32 v213, v213
	v_rcp_f32_e32 v214, v214
	v_rcp_f32_e32 v215, v215
	v_rcp_f32_e32 v216, v216
	v_rcp_f32_e32 v217, v217
	v_pk_mul_f32 v[210:211], v[60:61], v[210:211]
	v_pk_mul_f32 v[212:213], v[62:63], v[212:213]
	v_pk_mul_f32 v[214:215], v[52:53], v[214:215]
	v_pk_mul_f32 v[216:217], v[54:55], v[216:217]
	v_pk_mul_f32 v[218:219], v[210:211], v[56:57]
	v_pk_mul_f32 v[220:221], v[212:213], v[58:59]
	v_pk_mul_f32 v[222:223], v[214:215], v[48:49]
	v_pk_mul_f32 v[224:225], v[216:217], v[50:51]
	v_add_u32_e32 v64, 0x80, v138
	v_mad_i64_i32 v[52:53], s[42:43], v64, s19, v[128:129]
	v_cvt_pk_bf16_f32 v48, v218, v219
	v_cvt_pk_bf16_f32 v49, v220, v221
	v_cvt_pk_bf16_f32 v50, v222, v223
	v_cvt_pk_bf16_f32 v51, v224, v225
	global_store_dwordx4 v[52:53], v[48:51], off
	s_nop 1
	v_pk_mul_f32 v[210:211], v[44:45], v[228:229] op_sel_hi:[1,0]
	v_pk_mul_f32 v[212:213], v[46:47], v[228:229] op_sel_hi:[1,0]
	v_pk_mul_f32 v[214:215], v[36:37], v[228:229] op_sel_hi:[1,0]
	v_pk_mul_f32 v[216:217], v[38:39], v[228:229] op_sel_hi:[1,0]
	v_exp_f32_e32 v210, v210
	v_exp_f32_e32 v211, v211
	v_exp_f32_e32 v212, v212
	v_exp_f32_e32 v213, v213
	v_exp_f32_e32 v214, v214
	v_exp_f32_e32 v215, v215
	v_exp_f32_e32 v216, v216
	v_exp_f32_e32 v217, v217
	v_pk_add_f32 v[210:211], v[210:211], 1.0 op_sel_hi:[1,0]
	v_pk_add_f32 v[212:213], v[212:213], 1.0 op_sel_hi:[1,0]
	v_pk_add_f32 v[214:215], v[214:215], 1.0 op_sel_hi:[1,0]
	v_pk_add_f32 v[216:217], v[216:217], 1.0 op_sel_hi:[1,0]
	v_rcp_f32_e32 v210, v210
	v_rcp_f32_e32 v211, v211
	v_rcp_f32_e32 v212, v212
	v_rcp_f32_e32 v213, v213
	v_rcp_f32_e32 v214, v214
	v_rcp_f32_e32 v215, v215
	v_rcp_f32_e32 v216, v216
	v_rcp_f32_e32 v217, v217
	v_pk_mul_f32 v[210:211], v[44:45], v[210:211]
	v_pk_mul_f32 v[212:213], v[46:47], v[212:213]
	v_pk_mul_f32 v[214:215], v[36:37], v[214:215]
	v_pk_mul_f32 v[216:217], v[38:39], v[216:217]
	v_pk_mul_f32 v[218:219], v[210:211], v[40:41]
; __device__ __forceinline__ unsigned pk2(float lo, float hi) { return pg8::cvt_pk_bf16(lo, hi); }
; __device__ __forceinline__ float sigm(float x) { return __builtin_amdgcn_rcpf(1.f + __expf(-x)); }
;     __device__ __forceinline__ void operator()(const f32x4 (&acc)[2][2][4][2], const pg8::Unit& u, int wr, int wc, int fr, int fq) const {
;     ...
;         const int row0 = u.pm * 256 + wr * 64 + fr, col0 = u.pn * 128 + wc * 32 + 8 * fq;
; #pragma unroll
;         for (int ai = 0; ai < 2; ++ai)
; #pragma unroll
;             for (int m = 0; m < 4; ++m) {
;                 bf16_t* rowp = O + (size_t)(row0 + ai * 128 + m * 16) * DFF + col0;
;                 float v[8];
; #pragma unroll
;                 for (int n = 0; n < 2; ++n)
; #pragma unroll
;                     for (int j = 0; j < 4; ++j) { const float g = acc[ai][0][m][n][j], up = acc[ai][1][m][n][j]; v[n * 4 + j] = g * sigm(g) * up; }
;                 u32x4 w; w.x = pk2(v[0], v[1]); w.y = pk2(v[2], v[3]); w.z = pk2(v[4], v[5]); w.w = pk2(v[6], v[7]);
;                 *(u32x4*)rowp = w;
;             }
	v_pk_mul_f32 v[220:221], v[212:213], v[42:43]
	v_pk_mul_f32 v[222:223], v[214:215], v[32:33]
	v_pk_mul_f32 v[224:225], v[216:217], v[34:35]
	v_add_u32_e32 v48, 0x90, v138
	v_mad_i64_i32 v[36:37], s[42:43], v48, s19, v[128:129]
	v_cvt_pk_bf16_f32 v32, v218, v219
	v_cvt_pk_bf16_f32 v33, v220, v221
	v_cvt_pk_bf16_f32 v34, v222, v223
	v_cvt_pk_bf16_f32 v35, v224, v225
	global_store_dwordx4 v[36:37], v[32:35], off
	s_nop 1
	v_pk_mul_f32 v[210:211], v[28:29], v[228:229] op_sel_hi:[1,0]
	v_pk_mul_f32 v[212:213], v[30:31], v[228:229] op_sel_hi:[1,0]
	v_pk_mul_f32 v[214:215], v[20:21], v[228:229] op_sel_hi:[1,0]
	v_pk_mul_f32 v[216:217], v[22:23], v[228:229] op_sel_hi:[1,0]
	v_exp_f32_e32 v210, v210
	v_exp_f32_e32 v211, v211
	v_exp_f32_e32 v212, v212
	v_exp_f32_e32 v213, v213
	v_exp_f32_e32 v214, v214
	v_exp_f32_e32 v215, v215
	v_exp_f32_e32 v216, v216
	v_exp_f32_e32 v217, v217
	v_pk_add_f32 v[210:211], v[210:211], 1.0 op_sel_hi:[1,0]
	v_pk_add_f32 v[212:213], v[212:213], 1.0 op_sel_hi:[1,0]
	v_pk_add_f32 v[214:215], v[214:215], 1.0 op_sel_hi:[1,0]
	v_pk_add_f32 v[216:217], v[216:217], 1.0 op_sel_hi:[1,0]
	v_rcp_f32_e32 v210, v210
	v_rcp_f32_e32 v211, v211
	v_rcp_f32_e32 v212, v212
	v_rcp_f32_e32 v213, v213
	v_rcp_f32_e32 v214, v214
	v_rcp_f32_e32 v215, v215
	v_rcp_f32_e32 v216, v216
	v_rcp_f32_e32 v217, v217
	v_pk_mul_f32 v[210:211], v[28:29], v[210:211]
	v_pk_mul_f32 v[212:213], v[30:31], v[212:213]
	v_pk_mul_f32 v[214:215], v[20:21], v[214:215]
	v_pk_mul_f32 v[216:217], v[22:23], v[216:217]
	v_pk_mul_f32 v[218:219], v[210:211], v[24:25]
	v_pk_mul_f32 v[220:221], v[212:213], v[26:27]
	v_pk_mul_f32 v[222:223], v[214:215], v[16:17]
	v_pk_mul_f32 v[224:225], v[216:217], v[18:19]
	v_add_u32_e32 v32, 0xa0, v138
	v_mad_i64_i32 v[20:21], s[42:43], v32, s19, v[128:129]
	v_cvt_pk_bf16_f32 v16, v218, v219
	v_cvt_pk_bf16_f32 v17, v220, v221
	v_cvt_pk_bf16_f32 v18, v222, v223
	v_cvt_pk_bf16_f32 v19, v224, v225
	global_store_dwordx4 v[20:21], v[16:19], off
	s_nop 1
	v_pk_mul_f32 v[210:211], v[12:13], v[228:229] op_sel_hi:[1,0]
	v_pk_mul_f32 v[212:213], v[14:15], v[228:229] op_sel_hi:[1,0]
	v_pk_mul_f32 v[214:215], v[4:5], v[228:229] op_sel_hi:[1,0]
	v_pk_mul_f32 v[216:217], v[6:7], v[228:229] op_sel_hi:[1,0]
	v_exp_f32_e32 v210, v210
	v_exp_f32_e32 v211, v211
	v_exp_f32_e32 v212, v212
	v_exp_f32_e32 v213, v213
	v_exp_f32_e32 v214, v214
	v_exp_f32_e32 v215, v215
	v_exp_f32_e32 v216, v216
	v_exp_f32_e32 v217, v217
	v_pk_add_f32 v[210:211], v[210:211], 1.0 op_sel_hi:[1,0]
	v_pk_add_f32 v[212:213], v[212:213], 1.0 op_sel_hi:[1,0]
	v_pk_add_f32 v[214:215], v[214:215], 1.0 op_sel_hi:[1,0]
	v_pk_add_f32 v[216:217], v[216:217], 1.0 op_sel_hi:[1,0]
	v_rcp_f32_e32 v210, v210
	v_rcp_f32_e32 v211, v211
	v_rcp_f32_e32 v212, v212
	v_rcp_f32_e32 v213, v213
	v_rcp_f32_e32 v214, v214
	v_rcp_f32_e32 v215, v215
	v_rcp_f32_e32 v216, v216
	v_rcp_f32_e32 v217, v217
	v_pk_mul_f32 v[210:211], v[12:13], v[210:211]
	v_pk_mul_f32 v[212:213], v[14:15], v[212:213]
	v_pk_mul_f32 v[214:215], v[4:5], v[214:215]
	v_pk_mul_f32 v[216:217], v[6:7], v[216:217]
	v_pk_mul_f32 v[218:219], v[210:211], v[8:9]
	v_pk_mul_f32 v[220:221], v[212:213], v[10:11]
	v_pk_mul_f32 v[222:223], v[214:215], v[0:1]
	v_pk_mul_f32 v[224:225], v[216:217], v[2:3]
	v_add_u32_e32 v16, 0xb0, v138
	v_mad_i64_i32 v[4:5], s[42:43], v16, s19, v[128:129]
	s_mov_b64 s[42:43], -1
	v_cvt_pk_bf16_f32 v0, v218, v219
	v_cvt_pk_bf16_f32 v1, v220, v221
	v_cvt_pk_bf16_f32 v2, v222, v223
	v_cvt_pk_bf16_f32 v3, v224, v225
	global_store_dwordx4 v[4:5], v[0:3], off
	s_nop 1
	s_cbranch_vccnz .LBB0_465
	s_andn2_b64 vcc, exec, s[24:25]
	s_cbranch_vccnz .LBB0_464
	s_barrier
	s_branch .LBB0_464
